# grid-barrier spin back-off s_sleep 4 in every poll loop
# baseline (speedup 1.0000x reference)
; __global__ void __launch_bounds__(512, 2) mk_fwd(Args args) {
;     ...
;     if (hi > NPHASE) grid.sync();
.LBB0_18:
	s_sleep 4
	global_load_dword v2, v0, s[0:1] offset:32 sc1
	s_waitcnt vmcnt(0)
	v_and_b32_e32 v2, 0xffff0000, v2
	v_cmp_ne_u32_e32 vcc, v2, v1
	s_or_b64 s[6:7], vcc, s[6:7]
	s_andn2_b64 exec, exec, s[6:7]
	s_cbranch_execnz .LBB0_18

; __device__ __forceinline__ unsigned xb_ld(unsigned* p)              { return __hip_atomic_load(p, __ATOMIC_RELAXED, __HIP_MEMORY_SCOPE_AGENT); }
; __device__ __forceinline__ void xcd_barrier_complete(unsigned* bar, unsigned x, unsigned& nloc, unsigned& nx) {
;     const unsigned G = gridDim.x * gridDim.y * gridDim.z;
;     unsigned sum, cnt, mine, sp = 0u;
;     for (;;) {
;         sum = 0u; cnt = 0u; mine = 0u;
; #pragma unroll
;         for (unsigned j = 0; j < 16; ++j) { const unsigned c = xb_ld(&bar[XB_XCNT(j)]); sum += c; cnt += (c > 0u) ? 1u : 0u; mine = (j == x) ? c : mine; }
;         if (sum == G) break;
;         __builtin_amdgcn_s_sleep(1);
;         if ((++sp & 255u) == 0u) { if (xb_ld(&bar[XB_TMO])) break; if (sp > XB_SPIN_CAP) { atomicAdd(&bar[XB_TMO], 1u); break; } }
;     }
.LBB0_72:
	global_load_dword v15, v16, s[8:9] sc1
	s_waitcnt lgkmcnt(0)
	global_load_dword v0, v16, s[10:11] sc1
	global_load_dword v1, v16, s[14:15] sc1
	global_load_dword v2, v16, s[16:17] sc1
	global_load_dword v3, v16, s[18:19] sc1
	global_load_dword v4, v16, s[20:21] sc1
	global_load_dword v5, v16, s[22:23] sc1
	global_load_dword v6, v16, s[24:25] sc1
	global_load_dword v7, v16, s[26:27] sc1
	global_load_dword v8, v16, s[28:29] sc1
	global_load_dword v9, v16, s[30:31] sc1
	global_load_dword v10, v16, s[34:35] sc1
	global_load_dword v11, v16, s[36:37] sc1
	global_load_dword v12, v16, s[38:39] sc1
	global_load_dword v13, v16, s[40:41] sc1
	global_load_dword v14, v16, s[42:43] sc1
	s_mov_b64 s[44:45], -1
	s_mov_b64 s[48:49], -1
	s_waitcnt vmcnt(14)
	v_add_u32_e32 v17, v0, v15
	s_waitcnt vmcnt(13)
	v_add_u32_e32 v17, v17, v1
	s_waitcnt vmcnt(12)
	v_add_u32_e32 v17, v17, v2
	s_waitcnt vmcnt(11)
	v_add_u32_e32 v17, v17, v3
	s_waitcnt vmcnt(10)
	v_add_u32_e32 v17, v17, v4
	s_waitcnt vmcnt(9)
	v_add_u32_e32 v17, v17, v5
	s_waitcnt vmcnt(8)
	v_add_u32_e32 v17, v17, v6
	s_waitcnt vmcnt(7)
	v_add_u32_e32 v17, v17, v7
	s_waitcnt vmcnt(6)
	v_add_u32_e32 v17, v17, v8
	s_waitcnt vmcnt(5)
	v_add_u32_e32 v17, v17, v9
	s_waitcnt vmcnt(4)
	v_add_u32_e32 v17, v17, v10
	s_waitcnt vmcnt(3)
	v_add_u32_e32 v17, v17, v11
	s_waitcnt vmcnt(2)
	v_add_u32_e32 v17, v17, v12
	s_waitcnt vmcnt(1)
	v_add_u32_e32 v17, v17, v13
	s_waitcnt vmcnt(0)
	v_add_u32_e32 v17, v17, v14
	v_cmp_eq_u32_e32 vcc, s52, v17
	s_cbranch_vccnz .LBB0_71
	s_and_b32 s44, s53, 0xff
	s_cmp_eq_u32 s44, 0
	s_mov_b64 s[44:45], -1
	s_mov_b64 s[50:51], -1
	s_sleep 4
	s_cbranch_scc0 .LBB0_76
	global_load_dword v17, v16, s[6:7] sc1
	s_waitcnt vmcnt(0)
	v_cmp_eq_u32_e32 vcc, 0, v17
	s_cbranch_vccnz .LBB0_78
	s_mov_b64 s[50:51], 0

.LBB0_90:
	s_and_b32 s24, s28, 0xff
	s_mov_b64 s[22:23], -1
	s_cmp_lg_u32 s24, 0
	s_mov_b64 s[26:27], -1
	s_sleep 4
	s_cbranch_scc1 .LBB0_93
	global_load_dword v2, v0, s[14:15] sc1
	s_waitcnt vmcnt(0)
	v_cmp_eq_u32_e32 vcc, 0, v2
	s_cbranch_vccnz .LBB0_95
	s_mov_b64 s[26:27], 0
	s_mov_b64 s[24:25], -1

.LBB0_107:
	s_and_b32 s22, s28, 0xff
	s_cmp_lg_u32 s22, 0
	s_mov_b64 s[24:25], -1
	s_sleep 4
	s_cbranch_scc1 .LBB0_110
	global_load_dword v1, v0, s[14:15] sc1
	s_waitcnt vmcnt(0)
	v_cmp_eq_u32_e32 vcc, 0, v1
	s_cbranch_vccnz .LBB0_112
	s_mov_b64 s[24:25], 0
	s_mov_b64 s[22:23], -1

; __device__ __forceinline__ unsigned xb_ld(unsigned* p)              { return __hip_atomic_load(p, __ATOMIC_RELAXED, __HIP_MEMORY_SCOPE_AGENT); }
; __device__ __forceinline__ void xcd_barrier_complete(unsigned* bar, unsigned x, unsigned& nloc, unsigned& nx) {
;     const unsigned G = gridDim.x * gridDim.y * gridDim.z;
;     unsigned sum, cnt, mine, sp = 0u;
;     for (;;) {
;         sum = 0u; cnt = 0u; mine = 0u;
; #pragma unroll
;         for (unsigned j = 0; j < 16; ++j) { const unsigned c = xb_ld(&bar[XB_XCNT(j)]); sum += c; cnt += (c > 0u) ? 1u : 0u; mine = (j == x) ? c : mine; }
;         if (sum == G) break;
;         __builtin_amdgcn_s_sleep(1);
;         if ((++sp & 255u) == 0u) { if (xb_ld(&bar[XB_TMO])) break; if (sp > XB_SPIN_CAP) { atomicAdd(&bar[XB_TMO], 1u); break; } }
;     }
.LBB0_180:
	v_readlane_b32 s6, v254, 8
	v_readlane_b32 s7, v254, 9
	global_load_dword v5, v193, s[88:89] sc1
	s_waitcnt lgkmcnt(0)
	global_load_dword v0, v193, s[90:91] sc1
	global_load_dword v1, v193, s[92:93] sc1
	global_load_dword v2, v193, s[76:77] sc1
	global_load_dword v3, v193, s[70:71] sc1
	global_load_dword v4, v193, s[72:73] sc1
	global_load_dword v6, v193, s[6:7] sc1
	v_readlane_b32 s6, v254, 10
	v_readlane_b32 s7, v254, 11
	s_mov_b64 s[38:39], -1
	s_mov_b64 s[40:41], -1
	s_waitcnt vmcnt(5)
	v_add_u32_e32 v16, v0, v5
	s_nop 0
	global_load_dword v7, v193, s[6:7] sc1
	v_readlane_b32 s6, v254, 12
	v_readlane_b32 s7, v254, 13
	s_waitcnt vmcnt(5)
	v_add_u32_e32 v16, v16, v1
	s_waitcnt vmcnt(4)
	v_add_u32_e32 v16, v16, v2
	s_waitcnt vmcnt(3)
	v_add_u32_e32 v16, v16, v3
	s_waitcnt vmcnt(2)
	v_add_u32_e32 v16, v16, v4
	s_waitcnt vmcnt(1)
	v_add_u32_e32 v16, v16, v6
	global_load_dword v8, v193, s[6:7] sc1
	v_readlane_b32 s6, v254, 14
	v_readlane_b32 s7, v254, 15
	s_waitcnt vmcnt(1)
	v_add_u32_e32 v16, v16, v7
	s_nop 2
	global_load_dword v9, v193, s[6:7] sc1
	v_readlane_b32 s6, v254, 16
	v_readlane_b32 s7, v254, 17
	s_waitcnt vmcnt(1)
	v_add_u32_e32 v16, v16, v8
	s_nop 2
	global_load_dword v10, v193, s[6:7] sc1
	v_readlane_b32 s6, v254, 18
	v_readlane_b32 s7, v254, 19
	s_waitcnt vmcnt(1)
	v_add_u32_e32 v16, v16, v9
	s_nop 2
	global_load_dword v11, v193, s[6:7] sc1
	v_readlane_b32 s6, v254, 20
	v_readlane_b32 s7, v254, 21
	s_waitcnt vmcnt(1)
	v_add_u32_e32 v16, v16, v10
	s_nop 2
	global_load_dword v12, v193, s[6:7] sc1
	v_readlane_b32 s6, v254, 22
	v_readlane_b32 s7, v254, 23
	s_waitcnt vmcnt(1)
	v_add_u32_e32 v16, v16, v11
	s_nop 2
	global_load_dword v13, v193, s[6:7] sc1
	v_readlane_b32 s6, v254, 24
	v_readlane_b32 s7, v254, 25
	s_waitcnt vmcnt(1)
	v_add_u32_e32 v16, v16, v12
	s_nop 2
	global_load_dword v14, v193, s[6:7] sc1
	v_readlane_b32 s6, v254, 26
	v_readlane_b32 s7, v254, 27
	s_waitcnt vmcnt(1)
	v_add_u32_e32 v16, v16, v13
	s_nop 2
	global_load_dword v15, v193, s[6:7] sc1
	s_waitcnt vmcnt(1)
	v_add_u32_e32 v16, v16, v14
	s_waitcnt vmcnt(0)
	v_add_u32_e32 v16, v16, v15
	v_cmp_eq_u32_e32 vcc, s26, v16
	s_cbranch_vccnz .LBB0_179
	s_and_b32 s6, s5, 0xff
	s_cmp_eq_u32 s6, 0
	s_mov_b64 s[42:43], -1
	s_sleep 4
	s_cbranch_scc0 .LBB0_184
	global_load_dword v16, v193, s[44:45] sc1
	s_waitcnt vmcnt(0)
	v_cmp_eq_u32_e32 vcc, 0, v16
	s_cbranch_vccnz .LBB0_186
	s_mov_b64 s[42:43], 0

.LBB0_199:
	s_and_b32 s6, s5, 0xff
	s_mov_b64 s[72:73], -1
	s_cmp_lg_u32 s6, 0
	s_mov_b64 s[76:77], -1
	s_sleep 4
	s_cbranch_scc1 .LBB0_202
	global_load_dword v0, v193, s[44:45] sc1
	s_waitcnt vmcnt(0)
	v_cmp_eq_u32_e32 vcc, 0, v0
	s_cbranch_vccnz .LBB0_204
	s_mov_b64 s[76:77], 0
	s_mov_b64 s[74:75], -1

; __device__ __forceinline__ unsigned xb_ld(unsigned* p)              { return __hip_atomic_load(p, __ATOMIC_RELAXED, __HIP_MEMORY_SCOPE_AGENT); }
; __device__ __forceinline__ void xcd_barrier_complete(unsigned* bar, unsigned x, unsigned& nloc, unsigned& nx) {
;     const unsigned G = gridDim.x * gridDim.y * gridDim.z;
;     unsigned sum, cnt, mine, sp = 0u;
;     for (;;) {
;         sum = 0u; cnt = 0u; mine = 0u;
; #pragma unroll
;         for (unsigned j = 0; j < 16; ++j) { const unsigned c = xb_ld(&bar[XB_XCNT(j)]); sum += c; cnt += (c > 0u) ? 1u : 0u; mine = (j == x) ? c : mine; }
;         if (sum == G) break;
;         __builtin_amdgcn_s_sleep(1);
;         if ((++sp & 255u) == 0u) { if (xb_ld(&bar[XB_TMO])) break; if (sp > XB_SPIN_CAP) { atomicAdd(&bar[XB_TMO], 1u); break; } }
;     }
.LBB0_308:
	v_readlane_b32 s2, v254, 8
	v_readlane_b32 s3, v254, 9
	global_load_dword v5, v193, s[88:89] sc1
	s_waitcnt lgkmcnt(0)
	global_load_dword v0, v193, s[90:91] sc1
	global_load_dword v1, v193, s[92:93] sc1
	global_load_dword v2, v193, s[76:77] sc1
	global_load_dword v3, v193, s[70:71] sc1
	global_load_dword v4, v193, s[72:73] sc1
	global_load_dword v6, v193, s[2:3] sc1
	v_readlane_b32 s2, v254, 10
	v_readlane_b32 s3, v254, 11
	s_mov_b64 s[38:39], -1
	s_waitcnt vmcnt(5)
	v_add_u32_e32 v16, v0, v5
	s_nop 1
	global_load_dword v7, v193, s[2:3] sc1
	v_readlane_b32 s2, v254, 12
	v_readlane_b32 s3, v254, 13
	s_waitcnt vmcnt(5)
	v_add_u32_e32 v16, v16, v1
	s_waitcnt vmcnt(4)
	v_add_u32_e32 v16, v16, v2
	s_waitcnt vmcnt(3)
	v_add_u32_e32 v16, v16, v3
	s_waitcnt vmcnt(2)
	v_add_u32_e32 v16, v16, v4
	s_waitcnt vmcnt(1)
	v_add_u32_e32 v16, v16, v6
	global_load_dword v8, v193, s[2:3] sc1
	v_readlane_b32 s2, v254, 14
	v_readlane_b32 s3, v254, 15
	s_waitcnt vmcnt(1)
	v_add_u32_e32 v16, v16, v7
	s_nop 2
	global_load_dword v9, v193, s[2:3] sc1
	v_readlane_b32 s2, v254, 16
	v_readlane_b32 s3, v254, 17
	s_waitcnt vmcnt(1)
	v_add_u32_e32 v16, v16, v8
	s_nop 2
	global_load_dword v10, v193, s[2:3] sc1
	v_readlane_b32 s2, v254, 18
	v_readlane_b32 s3, v254, 19
	s_waitcnt vmcnt(1)
	v_add_u32_e32 v16, v16, v9
	s_nop 2
	global_load_dword v11, v193, s[2:3] sc1
	v_readlane_b32 s2, v254, 20
	v_readlane_b32 s3, v254, 21
	s_waitcnt vmcnt(1)
	v_add_u32_e32 v16, v16, v10
	s_nop 2
	global_load_dword v12, v193, s[2:3] sc1
	v_readlane_b32 s2, v254, 22
	v_readlane_b32 s3, v254, 23
	s_waitcnt vmcnt(1)
	v_add_u32_e32 v16, v16, v11
	s_nop 2
	global_load_dword v13, v193, s[2:3] sc1
	v_readlane_b32 s2, v254, 24
	v_readlane_b32 s3, v254, 25
	s_waitcnt vmcnt(1)
	v_add_u32_e32 v16, v16, v12
	s_nop 2
	global_load_dword v14, v193, s[2:3] sc1
	v_readlane_b32 s2, v254, 26
	v_readlane_b32 s3, v254, 27
	s_waitcnt vmcnt(1)
	v_add_u32_e32 v16, v16, v13
	s_nop 2
	global_load_dword v15, v193, s[2:3] sc1
	s_mov_b64 s[2:3], -1
	s_waitcnt vmcnt(1)
	v_add_u32_e32 v16, v16, v14
	s_waitcnt vmcnt(0)
	v_add_u32_e32 v16, v16, v15
	v_cmp_eq_u32_e32 vcc, s26, v16
	s_cbranch_vccnz .LBB0_307
	s_and_b32 s2, s5, 0xff
	s_cmp_eq_u32 s2, 0
	s_mov_b64 s[2:3], -1
	s_mov_b64 s[40:41], -1
	s_sleep 4
	s_cbranch_scc0 .LBB0_312
	global_load_dword v16, v193, s[44:45] sc1
	s_waitcnt vmcnt(0)
	v_cmp_eq_u32_e32 vcc, 0, v16
	s_cbranch_vccnz .LBB0_314
	s_mov_b64 s[40:41], 0

.LBB0_326:
	s_and_b32 s6, s5, 0xff
	s_mov_b64 s[70:71], -1
	s_cmp_lg_u32 s6, 0
	s_mov_b64 s[74:75], -1
	s_sleep 4
	s_cbranch_scc1 .LBB0_329
	global_load_dword v0, v193, s[44:45] sc1
	s_waitcnt vmcnt(0)
	v_cmp_eq_u32_e32 vcc, 0, v0
	s_cbranch_vccnz .LBB0_331
	s_mov_b64 s[74:75], 0
	s_mov_b64 s[72:73], -1

; __device__ __forceinline__ unsigned xb_ld(unsigned* p)              { return __hip_atomic_load(p, __ATOMIC_RELAXED, __HIP_MEMORY_SCOPE_AGENT); }
; __device__ __forceinline__ void xcd_barrier_complete(unsigned* bar, unsigned x, unsigned& nloc, unsigned& nx) {
;     const unsigned G = gridDim.x * gridDim.y * gridDim.z;
;     unsigned sum, cnt, mine, sp = 0u;
;     for (;;) {
;         sum = 0u; cnt = 0u; mine = 0u;
; #pragma unroll
;         for (unsigned j = 0; j < 16; ++j) { const unsigned c = xb_ld(&bar[XB_XCNT(j)]); sum += c; cnt += (c > 0u) ? 1u : 0u; mine = (j == x) ? c : mine; }
;         if (sum == G) break;
;         __builtin_amdgcn_s_sleep(1);
;         if ((++sp & 255u) == 0u) { if (xb_ld(&bar[XB_TMO])) break; if (sp > XB_SPIN_CAP) { atomicAdd(&bar[XB_TMO], 1u); break; } }
;     }
.LBB0_749:
	v_readlane_b32 s2, v254, 8
	v_readlane_b32 s3, v254, 9
	global_load_dword v5, v193, s[88:89] sc1
	s_waitcnt lgkmcnt(0)
	global_load_dword v0, v193, s[90:91] sc1
	global_load_dword v1, v193, s[92:93] sc1
	global_load_dword v2, v193, s[76:77] sc1
	global_load_dword v3, v193, s[70:71] sc1
	global_load_dword v4, v193, s[72:73] sc1
	global_load_dword v6, v193, s[2:3] sc1
	v_readlane_b32 s2, v254, 10
	v_readlane_b32 s3, v254, 11
	s_mov_b64 s[38:39], -1
	s_waitcnt vmcnt(5)
	v_add_u32_e32 v16, v0, v5
	s_nop 1
	global_load_dword v7, v193, s[2:3] sc1
	v_readlane_b32 s2, v254, 12
	v_readlane_b32 s3, v254, 13
	s_waitcnt vmcnt(5)
	v_add_u32_e32 v16, v16, v1
	s_waitcnt vmcnt(4)
	v_add_u32_e32 v16, v16, v2
	s_waitcnt vmcnt(3)
	v_add_u32_e32 v16, v16, v3
	s_waitcnt vmcnt(2)
	v_add_u32_e32 v16, v16, v4
	s_waitcnt vmcnt(1)
	v_add_u32_e32 v16, v16, v6
	global_load_dword v8, v193, s[2:3] sc1
	v_readlane_b32 s2, v254, 14
	v_readlane_b32 s3, v254, 15
	s_waitcnt vmcnt(1)
	v_add_u32_e32 v16, v16, v7
	s_nop 2
	global_load_dword v9, v193, s[2:3] sc1
	v_readlane_b32 s2, v254, 16
	v_readlane_b32 s3, v254, 17
	s_waitcnt vmcnt(1)
	v_add_u32_e32 v16, v16, v8
	s_nop 2
	global_load_dword v10, v193, s[2:3] sc1
	v_readlane_b32 s2, v254, 18
	v_readlane_b32 s3, v254, 19
	s_waitcnt vmcnt(1)
	v_add_u32_e32 v16, v16, v9
	s_nop 2
	global_load_dword v11, v193, s[2:3] sc1
	v_readlane_b32 s2, v254, 20
	v_readlane_b32 s3, v254, 21
	s_waitcnt vmcnt(1)
	v_add_u32_e32 v16, v16, v10
	s_nop 2
	global_load_dword v12, v193, s[2:3] sc1
	v_readlane_b32 s2, v254, 22
	v_readlane_b32 s3, v254, 23
	s_waitcnt vmcnt(1)
	v_add_u32_e32 v16, v16, v11
	s_nop 2
	global_load_dword v13, v193, s[2:3] sc1
	v_readlane_b32 s2, v254, 24
	v_readlane_b32 s3, v254, 25
	s_waitcnt vmcnt(1)
	v_add_u32_e32 v16, v16, v12
	s_nop 2
	global_load_dword v14, v193, s[2:3] sc1
	v_readlane_b32 s2, v254, 26
	v_readlane_b32 s3, v254, 27
	s_waitcnt vmcnt(1)
	v_add_u32_e32 v16, v16, v13
	s_nop 2
	global_load_dword v15, v193, s[2:3] sc1
	s_mov_b64 s[2:3], -1
	s_waitcnt vmcnt(1)
	v_add_u32_e32 v16, v16, v14
	s_waitcnt vmcnt(0)
	v_add_u32_e32 v16, v16, v15
	v_cmp_eq_u32_e32 vcc, s26, v16
	s_cbranch_vccnz .LBB0_748
	s_and_b32 s2, s4, 0xff
	s_cmp_eq_u32 s2, 0
	s_mov_b64 s[2:3], -1
	s_mov_b64 s[40:41], -1
	s_sleep 4
	s_cbranch_scc0 .LBB0_753
	global_load_dword v16, v193, s[44:45] sc1
	s_waitcnt vmcnt(0)
	v_cmp_eq_u32_e32 vcc, 0, v16
	s_cbranch_vccnz .LBB0_755
	s_mov_b64 s[40:41], 0

.LBB0_767:
	s_and_b32 s5, s4, 0xff
	s_mov_b64 s[68:69], -1
	s_cmp_lg_u32 s5, 0
	s_mov_b64 s[72:73], -1
	s_sleep 4
	s_cbranch_scc1 .LBB0_770
	global_load_dword v0, v193, s[44:45] sc1
	s_waitcnt vmcnt(0)
	v_cmp_eq_u32_e32 vcc, 0, v0
	s_cbranch_vccnz .LBB0_772
	s_mov_b64 s[72:73], 0
	s_mov_b64 s[70:71], -1
